# gemm1 unit header waits only for the tail's DMA (vmcnt(8)) unless the previous unit was the gate tile
# baseline (speedup 1.0000x reference)
.LBB0_473:
	s_mov_b32 s101, s16
	s_mov_b32 s17, 0x4991000
	s_mov_b32 s16, 0x1e80000
	s_mov_b32 s31, 0x10991000
	s_mov_b32 s36, 0x1a80000
	s_andn2_b64 vcc, exec, s[28:29]
	s_cbranch_vccz .LBB0_668
.LBB0_474:
	v_mov_b32_e32 v67, v169
	s_mov_b32 s11, s8
	v_lshrrev_b32_e32 v69, 4, v67
	v_ashrrev_i32_e32 v71, 3, v67
	v_lshrrev_b32_e32 v77, 1, v67
	v_and_b32_e32 v80, 4, v69
	v_and_b32_e32 v81, 3, v71
	v_and_b32_e32 v73, 7, v67
	v_xor_b32_e32 v75, v71, v67
	v_and_b32_e32 v77, 16, v77
	v_and_b32_e32 v79, 8, v69
	v_or_b32_e32 v82, v80, v81
	v_lshlrev_b32_e32 v75, 4, v75
	v_or3_b32 v77, v77, v79, v82
	v_bitop3_b32 v79, v80, v73, v81 bitop3:0x36
	v_lshlrev_b32_e32 v71, 7, v71
	v_lshlrev_b32_e32 v79, 4, v79
	v_and_or_b32 v115, v75, s24, v71
	v_lshl_or_b32 v114, v77, 7, v79
	v_lshlrev_b32_e32 v35, 7, v67
	v_bfe_u32 v34, v67, 4, 2
	v_and_b32_e32 v36, 0x780, v35
	v_and_b32_e32 v116, 0x2780, v35
	v_bitop3_b32 v35, v69, v73, 3 bitop3:0x6c
	v_mov_b32_e32 v75, v1
	v_lshlrev_b32_e32 v117, 4, v35
	v_lshlrev_b32_e32 v35, 6, v67
	v_bitop3_b32 v34, v34, v73, 4 bitop3:0x36
	v_mov_b32_e32 v73, v1
	v_mov_b32_e32 v67, v1
	v_mov_b32_e32 v69, v1
	v_mov_b32_e32 v77, v1
	v_mov_b32_e32 v71, v1
	v_mov_b32_e32 v79, v1
	v_lshl_add_u64 v[100:101], v[74:75], 1, s[0:1]
	v_mov_b32_e32 v74, 0
	s_mov_b32 s16, s10
	v_and_or_b32 v118, v35, s30, v36
	v_lshlrev_b32_e32 v119, 4, v34
	v_lshl_add_u64 v[98:99], v[72:73], 1, s[0:1]
	v_lshl_add_u64 v[102:103], v[76:77], 1, s[0:1]
	v_lshl_add_u64 v[104:105], v[78:79], 1, s[0:1]
	v_lshlrev_b64 v[106:107], 1, v[0:1]
	s_waitcnt lgkmcnt(8)
	v_lshlrev_b64 v[108:109], 1, v[66:67]
	v_lshlrev_b64 v[110:111], 1, v[68:69]
	v_lshlrev_b64 v[112:113], 1, v[70:71]
	s_mov_b32 s8, -2
	s_mov_b64 s[28:29], s[34:35]
	v_mov_b32_e32 v75, v74
	v_mov_b32_e32 v76, v74
	v_mov_b32_e32 v77, v74
	v_mov_b32_e32 v62, v74
	v_mov_b32_e32 v63, v74
	v_mov_b32_e32 v64, v74
	v_mov_b32_e32 v65, v74
	v_mov_b32_e32 v66, v74
	v_mov_b32_e32 v67, v74
	v_mov_b32_e32 v68, v74
	v_mov_b32_e32 v69, v74
	v_mov_b32_e32 v58, v74
	v_mov_b32_e32 v59, v74
	v_mov_b32_e32 v60, v74
	v_mov_b32_e32 v61, v74
	v_mov_b32_e32 v70, v74
	v_mov_b32_e32 v71, v74
	v_mov_b32_e32 v72, v74
	v_mov_b32_e32 v73, v74
	v_mov_b32_e32 v54, v74
	v_mov_b32_e32 v55, v74
	v_mov_b32_e32 v56, v74
	v_mov_b32_e32 v57, v74
	v_mov_b32_e32 v78, v74
	v_mov_b32_e32 v79, v74
	v_mov_b32_e32 v80, v74
	v_mov_b32_e32 v81, v74
	v_mov_b32_e32 v50, v74
	v_mov_b32_e32 v51, v74
	v_mov_b32_e32 v52, v74
	v_mov_b32_e32 v53, v74
	v_mov_b32_e32 v82, v74
	v_mov_b32_e32 v83, v74
	v_mov_b32_e32 v84, v74
	v_mov_b32_e32 v85, v74
	v_mov_b32_e32 v46, v74
	v_mov_b32_e32 v47, v74
	v_mov_b32_e32 v48, v74
	v_mov_b32_e32 v49, v74
	v_mov_b32_e32 v86, v74
	v_mov_b32_e32 v87, v74
	v_mov_b32_e32 v88, v74
	v_mov_b32_e32 v89, v74
	v_mov_b32_e32 v42, v74
	v_mov_b32_e32 v43, v74
	v_mov_b32_e32 v44, v74
	v_mov_b32_e32 v45, v74
	v_mov_b32_e32 v90, v74
	v_mov_b32_e32 v91, v74
	v_mov_b32_e32 v92, v74
	v_mov_b32_e32 v93, v74
	v_mov_b32_e32 v38, v74
	v_mov_b32_e32 v39, v74
	v_mov_b32_e32 v40, v74
	v_mov_b32_e32 v41, v74
	v_mov_b32_e32 v94, v74
	v_mov_b32_e32 v95, v74
	v_mov_b32_e32 v96, v74
	v_mov_b32_e32 v97, v74
	v_mov_b32_e32 v34, v74
	v_mov_b32_e32 v35, v74
	v_mov_b32_e32 v36, v74
	v_mov_b32_e32 v37, v74
	s_cmpk_gt_u32 s101, 0xfff
	s_cbranch_scc1 .Lg1_w0
	s_waitcnt vmcnt(8)
	s_branch .Lg1_wd

.Lg1_wd:
	s_waitcnt lgkmcnt(0)
	s_barrier
	v_lshrrev_b32_e32 v218, 6, v169
	v_lshlrev_b32_e32 v218, 10, v218
	v_lshrrev_b32_e32 v219, 3, v169
	v_readfirstlane_b32 s100, v218
	v_and_b32_e32 v218, 3, v219
	v_bfe_u32 v220, v219, 4, 1
	v_lshl_or_b32 v218, v220, 2, v218
	v_bfe_u32 v220, v219, 2, 1
	v_lshl_or_b32 v218, v220, 3, v218
	v_bfe_u32 v220, v219, 3, 1
	v_lshl_or_b32 v218, v220, 4, v218
	v_sub_u32_e32 v218, v218, v219
	v_mul_i32_i24_e32 v218, 0x800, v218
	v_and_b32_e32 v219, 7, v219
	v_lshlrev_b32_e32 v219, 4, v219
	v_add_u32_e32 v206, 0x4991000, v106
	v_xor_b32_e32 v164, v206, v219
	v_mov_b32_e32 v207, v98
	v_add_u32_e32 v165, v207, v218
	v_xor_b32_e32 v165, v165, v219
	v_add_u32_e32 v208, 0x4991000, v108
	v_xor_b32_e32 v166, v208, v219
	v_mov_b32_e32 v209, v100
	v_add_u32_e32 v167, v209, v218
	v_xor_b32_e32 v167, v167, v219
	v_add_u32_e32 v214, 0x4991000, v110
	v_xor_b32_e32 v198, v214, v219
	v_mov_b32_e32 v215, v102
	v_add_u32_e32 v199, v215, v218
	v_xor_b32_e32 v199, v199, v219
	v_add_u32_e32 v216, 0x4991000, v112
	v_xor_b32_e32 v200, v216, v219
	v_mov_b32_e32 v217, v104
	v_add_u32_e32 v201, v217, v218
	v_xor_b32_e32 v201, v201, v219
